# add batched pool_scale loads in both pool epilogues (one wait instead of load-wait-store x4)
# speedup vs baseline: 1.0186x; 1.0025x over previous
; #define LAS __attribute__((address_space(3)))
; DEV unsigned pk2(float lo, float hi) { unsigned r; asm("v_cvt_pk_bf16_f32 %0, %1, %2" : "=v"(r) : "v"(lo), "v"(hi)); return r; }
; DEV void pool_phase(const Fr& F, int l, int it0, int stride) {
;     ...
;         { const int t = tid >> 2, part = tid & 3; const int p = p0 + t; const int lo = max(p - half, 0), hi = min(p + win - half, seqlen); const float rc = 1.f / (float)(hi - lo);
;           float s[16];
; #pragma unroll
;           for (int j = 0; j < 16; ++j) s[j] = 0.f;
;           for (int o = -half; o < half; ++o) {
; #pragma unroll
;               for (int j = 0; j < 16; ++j) s[j] += Zt[(t + 8 + o) * 64 + part * 16 + j]; }
; #pragma unroll
;           for (int j = 0; j < 16; j += 2) { const float a0 = s[j] * rc - Zt[(t + 8) * 64 + part * 16 + j], a1 = s[j + 1] * rc - Zt[(t + 8) * 64 + part * 16 + j + 1];
;               *(LAS unsigned*)(Dm + t * 72 + part * 16 + j) = pk2(a0, a1); } }
;         __syncthreads();
;         f32x4 acc[4];
; #pragma unroll
;         for (int nt = 0; nt < 4; ++nt) { acc[nt] = (f32x4){0.f, 0.f, 0.f, 0.f};
; #pragma unroll
;             for (int k0 = 0; k0 < 64; k0 += 32) { const bf16x8 xf = *(const LAS bf16x8*)(Dm + (16 * w + fr) * 72 + k0 + fq * 8); const bf16x8 yf = tr_frag(Wp, 72, k0, 16 * nt, F.lane);
;                 acc[nt] = __builtin_amdgcn_mfma_f32_16x16x32_bf16(yf, xf, acc[nt], 0, 0, 0); } }
;         { const int t = 16 * w + fr;
; #pragma unroll
;           for (int nt = 0; nt < 4; ++nt) { const int d0 = 16 * nt + 4 * fq; const f32x4 ps = *(const f32x4*)(F.in[I_POOLS] + l * 256 + g * 64 + d0);
;               u32x2 wv; wv.x = pk2(acc[nt][0] * ps[0], acc[nt][1] * ps[1]); wv.y = pk2(acc[nt][2] * ps[2], acc[nt][3] * ps[3]);
;               *(u32x2*)(F.MIX + (size_t)(row0 + t) * D + 768 + g * 64 + d0) = wv; } }
.LBB0_496:
	ds_read_b128 v[18:21], v1
	ds_read_b128 v[22:25], v1 offset:16
	ds_read_b128 v[26:29], v1 offset:32
	ds_read_b128 v[30:33], v1 offset:48
	s_add_i32 s58, s58, 1
	v_add_u32_e32 v1, 0x100, v1
	s_cmp_ge_i32 s58, s7
	s_waitcnt lgkmcnt(3)
	v_pk_add_f32 v[16:17], v[16:17], v[18:19]
	v_pk_add_f32 v[14:15], v[14:15], v[20:21]
	s_waitcnt lgkmcnt(2)
	v_pk_add_f32 v[12:13], v[12:13], v[22:23]
	v_pk_add_f32 v[10:11], v[10:11], v[24:25]
	s_waitcnt lgkmcnt(1)
	v_pk_add_f32 v[8:9], v[8:9], v[26:27]
	v_pk_add_f32 v[6:7], v[6:7], v[28:29]
	s_waitcnt lgkmcnt(0)
	v_pk_add_f32 v[4:5], v[4:5], v[30:31]
	v_pk_add_f32 v[2:3], v[2:3], v[32:33]
	s_cbranch_scc0 .LBB0_496
	v_add_u32_e32 v1, s57, v185
	v_subrev_u32_e32 v18, s7, v1
	v_add_u32_e32 v1, s6, v1
	v_subrev_u32_e32 v1, s7, v1
	v_max_i32_e32 v18, 0, v18
	v_min_i32_e32 v1, s56, v1
	v_sub_u32_e32 v1, v1, v18
	v_cvt_f32_i32_e32 v1, v1
	v_add_u32_e32 v30, 0x800, v186
	s_add_i32 s44, s44, s45
	s_lshl_b32 s60, s41, 8
	v_div_scale_f32 v18, s[6:7], v1, v1, 1.0
	v_rcp_f32_e32 v19, v18
	v_readlane_b32 s6, v239, 25
	v_readlane_b32 s7, v239, 26
	v_mov_b32_e32 v169, v0
	v_fma_f32 v20, -v18, v19, 1.0
	v_fmac_f32_e32 v19, v20, v19
	v_div_scale_f32 v20, vcc, 1.0, v1, 1.0
	v_mul_f32_e32 v21, v20, v19
	v_fma_f32 v22, -v18, v21, v20
	v_fmac_f32_e32 v21, v22, v19
	v_fma_f32 v18, -v18, v21, v20
	v_div_fmas_f32 v18, v18, v19, v21
	v_div_fixup_f32 v1, v18, v1, 1.0
	ds_read2_b64 v[18:21], v30 offset1:1
	ds_read2_b64 v[22:25], v30 offset0:2 offset1:3
	ds_read2_b64 v[26:29], v30 offset0:4 offset1:5
	ds_read2_b64 v[30:33], v30 offset0:6 offset1:7
	s_waitcnt lgkmcnt(3)
	v_fma_f32 v16, v1, v16, -v18
	v_fma_f32 v17, v1, v17, -v19
	v_fma_f32 v14, v1, v14, -v20
	v_fma_f32 v15, v1, v15, -v21
	s_waitcnt lgkmcnt(2)
	v_fma_f32 v12, v1, v12, -v22
	v_fma_f32 v13, v1, v13, -v23
	v_fma_f32 v10, v1, v10, -v24
	v_fma_f32 v11, v1, v11, -v25
	s_waitcnt lgkmcnt(1)
	v_fma_f32 v8, v1, v8, -v26
	v_fma_f32 v9, v1, v9, -v27
	v_fma_f32 v6, v1, v6, -v28
	v_fma_f32 v7, v1, v7, -v29
	s_waitcnt lgkmcnt(0)
	v_fma_f32 v4, v1, v4, -v30
	v_fma_f32 v5, v1, v5, -v31
	v_fma_f32 v2, v1, v2, -v32
	v_fma_f32 v1, v1, v3, -v33
	v_cvt_pk_bf16_f32 v14, v14, v15
	v_add_u32_e32 v15, 0x9000, v212
	v_cvt_pk_bf16_f32 v1, v2, v1
	v_cvt_pk_bf16_f32 v16, v16, v17
	v_cvt_pk_bf16_f32 v12, v12, v13
	v_cvt_pk_bf16_f32 v10, v10, v11
	v_cvt_pk_bf16_f32 v8, v8, v9
	v_cvt_pk_bf16_f32 v6, v6, v7
	v_cvt_pk_bf16_f32 v4, v4, v5
	ds_write2_b32 v15, v4, v1 offset0:6 offset1:7
	v_add_u32_e32 v1, v201, v202
	ds_write2_b32 v15, v16, v14 offset1:1
	ds_write2_b32 v15, v12, v10 offset0:2 offset1:3
	ds_write2_b32 v15, v8, v6 offset0:4 offset1:5
	s_waitcnt lgkmcnt(0)
	s_barrier
	ds_read_b128 v[2:5], v213 offset:36864
	ds_read_b64_tr_b16 v[8:9], v1 offset:55872
	ds_read_b64_tr_b16 v[6:7], v1 offset:55296
	ds_read_b64_tr_b16 v[10:11], v1 offset:55328
	ds_read_b128 v[14:17], v213 offset:36928
	ds_read_b64_tr_b16 v[18:19], v1 offset:59904
	ds_read_b64_tr_b16 v[20:21], v1 offset:60480
	ds_read_b64_tr_b16 v[12:13], v1 offset:55904
	s_waitcnt lgkmcnt(5)
	v_mfma_f32_16x16x32_bf16 v[6:9], v[6:9], v[2:5], 0
	s_waitcnt lgkmcnt(1)
	v_mfma_f32_16x16x32_bf16 v[18:21], v[18:21], v[14:17], v[6:9]
	s_waitcnt lgkmcnt(0)
	v_mfma_f32_16x16x32_bf16 v[6:9], v[10:13], v[2:5], 0
	ds_read_b64_tr_b16 v[10:11], v1 offset:59936
	ds_read_b64_tr_b16 v[12:13], v1 offset:60512
	s_waitcnt lgkmcnt(0)
	v_mfma_f32_16x16x32_bf16 v[10:13], v[10:13], v[14:17], v[6:9]
	s_nop 3
	ds_read_b64_tr_b16 v[6:7], v1 offset:55360
	ds_read_b64_tr_b16 v[8:9], v1 offset:55936
	ds_read_b64_tr_b16 v[22:23], v1 offset:59968
	ds_read_b64_tr_b16 v[24:25], v1 offset:60544
	s_waitcnt lgkmcnt(2)
	v_mfma_f32_16x16x32_bf16 v[6:9], v[6:9], v[2:5], 0
	s_waitcnt lgkmcnt(0)
	v_mfma_f32_16x16x32_bf16 v[6:9], v[22:25], v[14:17], v[6:9]
	ds_read_b64_tr_b16 v[22:23], v1 offset:55392
	ds_read_b64_tr_b16 v[24:25], v1 offset:55968
	s_waitcnt lgkmcnt(0)
	v_mfma_f32_16x16x32_bf16 v[2:5], v[22:25], v[2:5], 0
	ds_read_b64_tr_b16 v[22:23], v1 offset:60000
	ds_read_b64_tr_b16 v[24:25], v1 offset:60576
	s_waitcnt lgkmcnt(0)
	v_mfma_f32_16x16x32_bf16 v[2:5], v[22:25], v[14:17], v[2:5]
	v_add_u32_e32 v14, s44, v187
	v_ashrrev_i32_e32 v15, 31, v14
	v_lshl_add_u64 v[24:25], v[164:165], 0, s[60:61]
	v_lshlrev_b64 v[22:23], 11, v[14:15]
	global_load_dwordx4 v[14:17], v[24:25], off
	global_load_dwordx4 v[244:247], v[24:25], off offset:64
	global_load_dwordx4 v[248:251], v[24:25], off offset:128
	global_load_dwordx4 v[252:255], v[24:25], off offset:192
	s_lshl_b32 s60, s41, 7
	s_waitcnt vmcnt(0)
	v_mul_f32_e32 v1, v18, v14
	v_mul_f32_e32 v14, v19, v15
	v_cvt_pk_bf16_f32 v14, v1, v14
	v_mul_f32_e32 v1, v20, v16
	v_mul_f32_e32 v15, v21, v17
	v_lshl_add_u64 v[16:17], s[6:7], 0, v[22:23]
	v_lshl_add_u64 v[16:17], v[16:17], 0, s[60:61]
	v_lshl_add_u64 v[18:19], v[16:17], 0, v[168:169]
	v_cvt_pk_bf16_f32 v15, v1, v15
	global_store_dwordx2 v[18:19], v[14:15], off offset:1536
	s_mov_b64 s[6:7], -1
	v_mul_f32_e32 v1, v10, v244
	v_mul_f32_e32 v10, v11, v245
	v_mul_f32_e32 v11, v13, v247
	v_cvt_pk_bf16_f32 v10, v1, v10
	v_mul_f32_e32 v1, v12, v246
	v_cvt_pk_bf16_f32 v11, v1, v11
	global_store_dwordx2 v[18:19], v[10:11], off offset:1568
	v_mul_f32_e32 v1, v6, v248
	v_mul_f32_e32 v6, v7, v249
	v_mul_f32_e32 v7, v9, v251
	v_cvt_pk_bf16_f32 v6, v1, v6
	v_mul_f32_e32 v1, v8, v250
	v_cvt_pk_bf16_f32 v7, v1, v7
	global_store_dwordx2 v[18:19], v[6:7], off offset:1600
	v_mul_f32_e32 v1, v2, v252
	v_mul_f32_e32 v2, v3, v253
	v_mul_f32_e32 v3, v5, v255
	v_cvt_pk_bf16_f32 v2, v1, v2
	v_mul_f32_e32 v1, v4, v254
	v_cvt_pk_bf16_f32 v3, v1, v3
	global_store_dwordx2 v[18:19], v[2:3], off offset:1632
	s_barrier
	s_branch .LBB0_499

; #define LAS __attribute__((address_space(3)))
; DEV unsigned pk2(float lo, float hi) { unsigned r; asm("v_cvt_pk_bf16_f32 %0, %1, %2" : "=v"(r) : "v"(lo), "v"(hi)); return r; }
; DEV void pool_phase(const Fr& F, int l, int it0, int stride) {
;     ...
;         { const int t = tid >> 2, part = tid & 3; const int p = p0 + t; const int lo = max(p - half, 0), hi = min(p + win - half, seqlen); const float rc = 1.f / (float)(hi - lo);
;           float s[16];
; #pragma unroll
;           for (int j = 0; j < 16; ++j) s[j] = 0.f;
;           for (int o = -half; o < half; ++o) {
; #pragma unroll
;               for (int j = 0; j < 16; ++j) s[j] += Zt[(t + 8 + o) * 64 + part * 16 + j]; }
; #pragma unroll
;           for (int j = 0; j < 16; j += 2) { const float a0 = s[j] * rc - Zt[(t + 8) * 64 + part * 16 + j], a1 = s[j + 1] * rc - Zt[(t + 8) * 64 + part * 16 + j + 1];
;               *(LAS unsigned*)(Dm + t * 72 + part * 16 + j) = pk2(a0, a1); } }
;         __syncthreads();
;         f32x4 acc[4];
; #pragma unroll
;         for (int nt = 0; nt < 4; ++nt) { acc[nt] = (f32x4){0.f, 0.f, 0.f, 0.f};
; #pragma unroll
;             for (int k0 = 0; k0 < 64; k0 += 32) { const bf16x8 xf = *(const LAS bf16x8*)(Dm + (16 * w + fr) * 72 + k0 + fq * 8); const bf16x8 yf = tr_frag(Wp, 72, k0, 16 * nt, F.lane);
;                 acc[nt] = __builtin_amdgcn_mfma_f32_16x16x32_bf16(yf, xf, acc[nt], 0, 0, 0); } }
;         { const int t = 16 * w + fr;
; #pragma unroll
;           for (int nt = 0; nt < 4; ++nt) { const int d0 = 16 * nt + 4 * fq; const f32x4 ps = *(const f32x4*)(F.in[I_POOLS] + l * 256 + g * 64 + d0);
;               u32x2 wv; wv.x = pk2(acc[nt][0] * ps[0], acc[nt][1] * ps[1]); wv.y = pk2(acc[nt][2] * ps[2], acc[nt][3] * ps[3]);
;               *(u32x2*)(F.MIX + (size_t)(row0 + t) * D + 768 + g * 64 + d0) = wv; } }
.LBB0_923:
	ds_read_b128 v[54:57], v27
	ds_read_b128 v[58:61], v27 offset:16
	ds_read_b128 v[62:65], v27 offset:32
	ds_read_b128 v[66:69], v27 offset:48
	s_add_i32 s6, s6, 1
	v_add_u32_e32 v27, 0x100, v27
	s_cmp_ge_i32 s6, s20
	s_waitcnt lgkmcnt(3)
	v_pk_add_f32 v[38:39], v[38:39], v[54:55]
	v_pk_add_f32 v[36:37], v[36:37], v[56:57]
	s_waitcnt lgkmcnt(2)
	v_pk_add_f32 v[24:25], v[24:25], v[58:59]
	v_pk_add_f32 v[22:23], v[22:23], v[60:61]
	s_waitcnt lgkmcnt(1)
	v_pk_add_f32 v[20:21], v[20:21], v[62:63]
	v_pk_add_f32 v[18:19], v[18:19], v[64:65]
	s_waitcnt lgkmcnt(0)
	v_pk_add_f32 v[16:17], v[16:17], v[66:67]
	v_pk_add_f32 v[14:15], v[14:15], v[68:69]
	s_cbranch_scc0 .LBB0_923
	s_ashr_i32 s6, s19, 2
	s_mul_hi_i32 s21, s6, 0x7e07e07f
	s_lshr_b32 s22, s21, 31
	s_ashr_i32 s21, s21, 6
	s_add_i32 s21, s21, s22
	s_mulk_i32 s21, 0x82
	s_sub_i32 s21, s6, s21
	s_lshl_b32 s6, s21, 7
	s_add_i32 s22, s6, 0xffffff00
	s_cmp_lt_i32 s21, 2
	s_cselect_b32 s22, s6, s22
	v_add_u32_e32 v27, s22, v42
	s_movk_i32 s21, 0x4000
	v_subrev_u32_e32 v35, s20, v27
	v_add_u32_e32 v27, s7, v27
	s_cselect_b32 s21, 0x100, s21
	v_subrev_u32_e32 v27, s20, v27
	v_max_i32_e32 v35, 0, v35
	v_min_i32_e32 v27, s21, v27
	v_sub_u32_e32 v27, v27, v35
	v_cvt_f32_i32_e32 v27, v27
	s_mul_hi_i32 s7, s19, 0x7e07e07f
	s_lshr_b32 s19, s7, 31
	s_lshr_b32 s7, s7, 8
	v_div_scale_f32 v35, s[20:21], v27, v27, 1.0
	v_rcp_f32_e32 v54, v35
	s_add_i32 s7, s7, s19
	s_mulk_i32 s7, 0x4100
	s_add_i32 s6, s6, s7
	v_fma_f32 v55, -v35, v54, 1.0
	v_fmac_f32_e32 v54, v55, v54
	v_div_scale_f32 v55, vcc, 1.0, v27, 1.0
	v_mul_f32_e32 v56, v55, v54
	v_fma_f32 v57, -v35, v56, v55
	v_fmac_f32_e32 v56, v57, v54
	v_fma_f32 v35, -v35, v56, v55
	v_div_fmas_f32 v35, v35, v54, v56
	v_div_fixup_f32 v27, v35, v27, 1.0
	v_add_u32_e32 v35, 0x800, v43
	ds_read2_b64 v[54:57], v35 offset1:1
	ds_read2_b64 v[58:61], v35 offset0:2 offset1:3
	ds_read2_b64 v[62:65], v35 offset0:4 offset1:5
	ds_read2_b64 v[66:69], v35 offset0:6 offset1:7
	s_lshl_b32 s60, s15, 6
	s_waitcnt lgkmcnt(3)
	v_fma_f32 v36, v27, v36, -v56
	v_fma_f32 v37, v27, v37, -v57
	s_waitcnt lgkmcnt(2)
	v_fma_f32 v24, v27, v24, -v58
	v_fma_f32 v22, v27, v22, -v60
	s_waitcnt lgkmcnt(1)
	v_fma_f32 v20, v27, v20, -v62
	v_fma_f32 v18, v27, v18, -v64
	s_waitcnt lgkmcnt(0)
	v_fma_f32 v16, v27, v16, -v66
	v_fma_f32 v14, v27, v14, -v68
	v_fma_f32 v35, v27, v38, -v54
	v_fma_f32 v38, v27, v39, -v55
	v_cvt_pk_bf16_f32 v36, v36, v37
	v_add_u32_e32 v37, 0x9000, v51
	v_fma_f32 v25, v27, v25, -v59
	v_cvt_pk_bf16_f32 v24, v24, v25
	v_fma_f32 v23, v27, v23, -v61
	v_cvt_pk_bf16_f32 v22, v22, v23
	v_fma_f32 v21, v27, v21, -v63
	v_cvt_pk_bf16_f32 v20, v20, v21
	v_fma_f32 v19, v27, v19, -v65
	v_cvt_pk_bf16_f32 v18, v18, v19
	v_fma_f32 v17, v27, v17, -v67
	v_cvt_pk_bf16_f32 v16, v16, v17
	v_fma_f32 v15, v27, v15, -v69
	v_cvt_pk_bf16_f32 v14, v14, v15
	v_cvt_pk_bf16_f32 v35, v35, v38
	ds_write2_b32 v37, v35, v36 offset1:1
	ds_write2_b32 v37, v24, v22 offset0:2 offset1:3
	ds_write2_b32 v37, v20, v18 offset0:4 offset1:5
	ds_write2_b32 v37, v16, v14 offset0:6 offset1:7
	s_waitcnt lgkmcnt(0)
	s_barrier
	ds_read_b128 v[14:17], v52 offset:36864
	ds_read_b64_tr_b16 v[20:21], v53 offset:55872
	ds_read_b64_tr_b16 v[18:19], v53 offset:55296
	ds_read_b64_tr_b16 v[22:23], v53 offset:55328
	ds_read_b128 v[36:39], v52 offset:36928
	ds_read_b64_tr_b16 v[54:55], v53 offset:59904
	ds_read_b64_tr_b16 v[56:57], v53 offset:60480
	ds_read_b64_tr_b16 v[24:25], v53 offset:55904
	s_waitcnt lgkmcnt(5)
	v_mfma_f32_16x16x32_bf16 v[18:21], v[18:21], v[14:17], 0
	s_and_b64 vcc, exec, s[16:17]
	s_mov_b32 s19, s18
	s_waitcnt lgkmcnt(1)
	v_mfma_f32_16x16x32_bf16 v[54:57], v[54:57], v[36:39], v[18:21]
	s_waitcnt lgkmcnt(0)
	v_mfma_f32_16x16x32_bf16 v[18:21], v[22:25], v[14:17], 0
	ds_read_b64_tr_b16 v[22:23], v53 offset:59936
	ds_read_b64_tr_b16 v[24:25], v53 offset:60512
	s_waitcnt lgkmcnt(0)
	v_mfma_f32_16x16x32_bf16 v[22:25], v[22:25], v[36:39], v[18:21]
	s_nop 3
	ds_read_b64_tr_b16 v[18:19], v53 offset:55360
	ds_read_b64_tr_b16 v[20:21], v53 offset:55936
	ds_read_b64_tr_b16 v[58:59], v53 offset:59968
	ds_read_b64_tr_b16 v[60:61], v53 offset:60544
	s_waitcnt lgkmcnt(2)
	v_mfma_f32_16x16x32_bf16 v[18:21], v[18:21], v[14:17], 0
	s_waitcnt lgkmcnt(0)
	v_mfma_f32_16x16x32_bf16 v[18:21], v[58:61], v[36:39], v[18:21]
	ds_read_b64_tr_b16 v[58:59], v53 offset:55392
	ds_read_b64_tr_b16 v[60:61], v53 offset:55968
	s_waitcnt lgkmcnt(0)
	v_mfma_f32_16x16x32_bf16 v[14:17], v[58:61], v[14:17], 0
	ds_read_b64_tr_b16 v[58:59], v53 offset:60000
	ds_read_b64_tr_b16 v[60:61], v53 offset:60576
	s_waitcnt lgkmcnt(0)
	v_mfma_f32_16x16x32_bf16 v[14:17], v[58:61], v[36:39], v[14:17]
	v_add_u32_e32 v36, s6, v44
	v_ashrrev_i32_e32 v37, 31, v36
	v_lshlrev_b64 v[38:39], 11, v[36:37]
	v_lshl_add_u64 v[36:37], s[60:61], 2, v[32:33]
	global_load_dwordx4 v[58:61], v[36:37], off
	global_load_dwordx4 v[244:247], v[36:37], off offset:64
	global_load_dwordx4 v[248:251], v[36:37], off offset:128
	global_load_dwordx4 v[252:255], v[36:37], off offset:192
	v_lshl_add_u64 v[38:39], s[80:81], 0, v[38:39]
	s_lshl_b32 s60, s15, 7
	v_lshl_add_u64 v[38:39], v[38:39], 0, s[60:61]
	s_waitcnt vmcnt(0)
	v_mul_f32_e32 v35, v55, v59
	v_mul_f32_e32 v27, v54, v58
	v_cvt_pk_bf16_f32 v54, v27, v35
	v_mul_f32_e32 v35, v57, v61
	v_mul_f32_e32 v27, v56, v60
	v_cvt_pk_bf16_f32 v55, v27, v35
	v_mov_b32_e32 v35, v0
	v_lshl_add_u64 v[38:39], v[38:39], 0, v[34:35]
	global_store_dwordx2 v[38:39], v[54:55], off offset:1536
	v_mul_f32_e32 v22, v22, v244
	v_mul_f32_e32 v23, v23, v245
	v_cvt_pk_bf16_f32 v22, v22, v23
	v_mul_f32_e32 v23, v24, v246
	v_mul_f32_e32 v24, v25, v247
	v_cvt_pk_bf16_f32 v23, v23, v24
	global_store_dwordx2 v[38:39], v[22:23], off offset:1568
	v_mul_f32_e32 v18, v18, v248
	v_mul_f32_e32 v19, v19, v249
	v_cvt_pk_bf16_f32 v18, v18, v19
	v_mul_f32_e32 v19, v20, v250
	v_mul_f32_e32 v20, v21, v251
	v_cvt_pk_bf16_f32 v19, v19, v20
	global_store_dwordx2 v[38:39], v[18:19], off offset:1600
	v_mul_f32_e32 v14, v14, v252
	v_mul_f32_e32 v15, v15, v253
	v_cvt_pk_bf16_f32 v14, v14, v15
	v_mul_f32_e32 v15, v16, v254
	v_mul_f32_e32 v16, v17, v255
	v_cvt_pk_bf16_f32 v15, v15, v16
	global_store_dwordx2 v[38:39], v[14:15], off offset:1632
	s_barrier
	s_cbranch_vccz .LBB0_902
